# scan2 carry-fold loops pipelined 5 deep (was 4)
# baseline (speedup 1.0000x reference)
; __device__ __forceinline__ void rg_fold8(const float* CAR, int b, int d, int ncar, int cg, float* h) {
; #pragma unroll
;     for (int e = 0; e < 8; ++e) h[e] = 0.f;
;     for (int c = 0; c < ncar; ++c) { const float* cp = CAR + ((size_t)((b * 2 + d) * 72 + c) * 160 + cg) * 16; const f32x4 p0 = *(const f32x4*)cp, p1 = *(const f32x4*)(cp + 4), s0 = *(const f32x4*)(cp + 8), s1 = *(const f32x4*)(cp + 12);
; #pragma unroll
;         for (int e = 0; e < 4; ++e) { h[e] = p0[e] * h[e] + s0[e]; h[4 + e] = p1[e] * h[4 + e] + s1[e]; } }
; }
; __device__ __forceinline__ void rg_scan2_phase(const bf16_t* RA0, bf16_t* RI0, const bf16_t* RA1, const bf16_t* RI1, const bf16_t* XCV, const float* bap, const float* bxp, const float* lamp, const float* CAR, bf16_t* Gb, int gtid, int ngt) {
;     for (int it = gtid; it < NB * 36 * 160; it += ngt) { const int cg = it % 160, tc = (it / 160) % 36, b = it / (160 * 36);
;         const int row0 = tc < 4 ? ML + b * CTX + 64 * tc : b * SEQ + 64 * (tc - 4);
;         const int cbk = tc < 4 ? 3 - tc : 4 + (35 - tc);
;         float h[8], ba[8], bx[8], sp[8];
;         rg_fold8(CAR, b, 0, 2 * tc, cg, h); rg_consts8(bap, bxp, lamp, 8 * cg, ba, bx, sp);
.LBB0_1209:
	v_mul_hi_i32 v0, v72, s43
	v_lshrrev_b32_e32 v1, 31, v0
	v_ashrrev_i32_e32 v0, 6, v0
	v_add_u32_e32 v0, v0, v1
	v_mul_hi_i32 v1, v0, s49
	v_lshrrev_b32_e32 v2, 31, v1
	v_ashrrev_i32_e32 v1, 3, v1
	v_add_u32_e32 v1, v1, v2
	v_mul_lo_u32 v1, v1, 36
	v_sub_u32_e32 v64, v0, v1
	v_mul_hi_i32 v1, v72, s44
	v_add_u32_e32 v1, v1, v72
	v_lshrrev_b32_e32 v2, 31, v1
	v_ashrrev_i32_e32 v1, 12, v1
	v_add_u32_e32 v65, v1, v2
	v_cmp_lt_i32_e32 vcc, 3, v64
	v_lshlrev_b32_e32 v1, 6, v64
	s_and_saveexec_b64 s[2:3], vcc
	s_xor_b64 s[6:7], exec, s[2:3]
	v_lshlrev_b32_e32 v2, 11, v65
	s_movk_i32 s1, 0xff00
	v_add3_u32 v22, v2, v1, s1
	s_or_saveexec_b64 s[6:7], s[6:7]
	v_mov_b32_e32 v66, 39
	s_xor_b64 exec, exec, s[6:7]
	v_lshlrev_b32_e32 v2, 8, v65
	v_add3_u32 v22, v2, v1, s40
	v_mov_b32_e32 v66, 3
	s_or_b64 exec, exec, s[6:7]
	v_mul_lo_u32 v0, v0, s41
	v_sub_u32_e32 v28, v72, v0
	v_cmp_lt_i32_e32 vcc, 0, v64
	v_mov_b32_e32 v58, 0
	v_ashrrev_i32_e32 v29, 31, v28
	v_mov_b32_e32 v52, 0
	v_mov_b32_e32 v46, 0
	v_mov_b32_e32 v48, 0
	v_mov_b32_e32 v50, 0
	v_mov_b32_e32 v44, 0
	v_mov_b32_e32 v42, 0
	v_mov_b32_e32 v40, 0
	s_and_saveexec_b64 s[6:7], vcc
	s_cbranch_execz .LBB0_1217
	v_mul_i32_i24_e32 v3, 0x90, v65
	v_lshlrev_b64 v[0:1], 6, v[28:29]
	s_movk_i32 s1, 0x2800
	v_mad_i64_i32 v[0:1], s[2:3], v3, s1, v[0:1]
	v_mov_b32_e32 v40, 0
	v_lshlrev_b32_e32 v2, 1, v64
	v_lshl_add_u64 v[0:1], s[20:21], 0, v[0:1]
	s_mov_b64 s[24:25], 0
	v_mov_b32_e32 v41, v40
	v_mov_b32_e32 v44, v40
	v_mov_b32_e32 v45, v40
	v_mov_b32_e32 v48, v40
	v_mov_b32_e32 v49, v40
	v_mov_b32_e32 v52, v40
	v_mov_b32_e32 v53, v40
	s_mov_b64 s[2:3], 0x2800
	global_load_dwordx4 v[96:99], v[0:1], off offset:48
	global_load_dwordx4 v[100:103], v[0:1], off offset:32
	global_load_dwordx4 v[104:107], v[0:1], off
	global_load_dwordx4 v[108:111], v[0:1], off offset:16
	v_lshl_add_u64 v[0:1], v[0:1], 0, s[2:3]
	global_load_dwordx4 v[112:115], v[0:1], off offset:48
	global_load_dwordx4 v[116:119], v[0:1], off offset:32
	global_load_dwordx4 v[120:123], v[0:1], off
	global_load_dwordx4 v[124:127], v[0:1], off offset:16
	v_lshl_add_u64 v[0:1], v[0:1], 0, s[2:3]
	global_load_dwordx4 v[128:131], v[0:1], off offset:48
	global_load_dwordx4 v[132:135], v[0:1], off offset:32
	global_load_dwordx4 v[136:139], v[0:1], off
	global_load_dwordx4 v[140:143], v[0:1], off offset:16
	v_lshl_add_u64 v[0:1], v[0:1], 0, s[2:3]
	global_load_dwordx4 v[144:147], v[0:1], off offset:48
	global_load_dwordx4 v[148:151], v[0:1], off offset:32
	global_load_dwordx4 v[152:155], v[0:1], off
	global_load_dwordx4 v[156:159], v[0:1], off offset:16
	v_lshl_add_u64 v[0:1], v[0:1], 0, s[2:3]
.LBB0_1215:
	global_load_dwordx4 v[168:171], v[0:1], off offset:48
	global_load_dwordx4 v[172:175], v[0:1], off offset:32
	global_load_dwordx4 v[176:179], v[0:1], off
	global_load_dwordx4 v[180:183], v[0:1], off offset:16
	v_add_u32_e32 v2, -1, v2
	v_cmp_eq_u32_e32 vcc, 0, v2
	v_lshl_add_u64 v[0:1], v[0:1], 0, s[2:3]
	s_or_b64 s[24:25], vcc, s[24:25]
	s_waitcnt vmcnt(16)
	v_pk_fma_f32 v[40:41], v[40:41], v[104:105], v[100:101]
	v_pk_fma_f32 v[48:49], v[48:49], v[108:109], v[96:97]
	v_pk_fma_f32 v[44:45], v[44:45], v[106:107], v[102:103]
	v_pk_fma_f32 v[52:53], v[52:53], v[110:111], v[98:99]
	s_andn2_b64 exec, exec, s[24:25]
	s_cbranch_execz .Lfold1_done
	global_load_dwordx4 v[96:99], v[0:1], off offset:48
	global_load_dwordx4 v[100:103], v[0:1], off offset:32
	global_load_dwordx4 v[104:107], v[0:1], off
	global_load_dwordx4 v[108:111], v[0:1], off offset:16
	v_add_u32_e32 v2, -1, v2
	v_cmp_eq_u32_e32 vcc, 0, v2
	v_lshl_add_u64 v[0:1], v[0:1], 0, s[2:3]
	s_or_b64 s[24:25], vcc, s[24:25]
	s_waitcnt vmcnt(16)
	v_pk_fma_f32 v[40:41], v[40:41], v[120:121], v[116:117]
	v_pk_fma_f32 v[48:49], v[48:49], v[124:125], v[112:113]
	v_pk_fma_f32 v[44:45], v[44:45], v[122:123], v[118:119]
	v_pk_fma_f32 v[52:53], v[52:53], v[126:127], v[114:115]
	s_andn2_b64 exec, exec, s[24:25]
	s_cbranch_execz .Lfold1_done
	global_load_dwordx4 v[112:115], v[0:1], off offset:48
	global_load_dwordx4 v[116:119], v[0:1], off offset:32
	global_load_dwordx4 v[120:123], v[0:1], off
	global_load_dwordx4 v[124:127], v[0:1], off offset:16
	v_add_u32_e32 v2, -1, v2
	v_cmp_eq_u32_e32 vcc, 0, v2
	v_lshl_add_u64 v[0:1], v[0:1], 0, s[2:3]
	s_or_b64 s[24:25], vcc, s[24:25]
	s_waitcnt vmcnt(16)
	v_pk_fma_f32 v[40:41], v[40:41], v[136:137], v[132:133]
	v_pk_fma_f32 v[48:49], v[48:49], v[140:141], v[128:129]
	v_pk_fma_f32 v[44:45], v[44:45], v[138:139], v[134:135]
	v_pk_fma_f32 v[52:53], v[52:53], v[142:143], v[130:131]
	s_andn2_b64 exec, exec, s[24:25]
	s_cbranch_execz .Lfold1_done
	global_load_dwordx4 v[128:131], v[0:1], off offset:48
	global_load_dwordx4 v[132:135], v[0:1], off offset:32
	global_load_dwordx4 v[136:139], v[0:1], off
	global_load_dwordx4 v[140:143], v[0:1], off offset:16
	v_add_u32_e32 v2, -1, v2
	v_cmp_eq_u32_e32 vcc, 0, v2
	v_lshl_add_u64 v[0:1], v[0:1], 0, s[2:3]
	s_or_b64 s[24:25], vcc, s[24:25]
	s_waitcnt vmcnt(16)
	v_pk_fma_f32 v[40:41], v[40:41], v[152:153], v[148:149]
	v_pk_fma_f32 v[48:49], v[48:49], v[156:157], v[144:145]
	v_pk_fma_f32 v[44:45], v[44:45], v[154:155], v[150:151]
	v_pk_fma_f32 v[52:53], v[52:53], v[158:159], v[146:147]
	s_andn2_b64 exec, exec, s[24:25]
	s_cbranch_execz .Lfold1_done
	global_load_dwordx4 v[144:147], v[0:1], off offset:48
	global_load_dwordx4 v[148:151], v[0:1], off offset:32
	global_load_dwordx4 v[152:155], v[0:1], off
	global_load_dwordx4 v[156:159], v[0:1], off offset:16
	v_add_u32_e32 v2, -1, v2
	v_cmp_eq_u32_e32 vcc, 0, v2
	v_lshl_add_u64 v[0:1], v[0:1], 0, s[2:3]
	s_or_b64 s[24:25], vcc, s[24:25]
	s_waitcnt vmcnt(16)
	v_pk_fma_f32 v[40:41], v[40:41], v[176:177], v[172:173]
	v_pk_fma_f32 v[48:49], v[48:49], v[180:181], v[168:169]
	v_pk_fma_f32 v[44:45], v[44:45], v[178:179], v[174:175]
	v_pk_fma_f32 v[52:53], v[52:53], v[182:183], v[170:171]
	s_andn2_b64 exec, exec, s[24:25]
	s_cbranch_execnz .LBB0_1215

; __device__ __forceinline__ void rg_fold8(const float* CAR, int b, int d, int ncar, int cg, float* h) {
; #pragma unroll
;     for (int e = 0; e < 8; ++e) h[e] = 0.f;
;     for (int c = 0; c < ncar; ++c) { const float* cp = CAR + ((size_t)((b * 2 + d) * 72 + c) * 160 + cg) * 16; const f32x4 p0 = *(const f32x4*)cp, p1 = *(const f32x4*)(cp + 4), s0 = *(const f32x4*)(cp + 8), s1 = *(const f32x4*)(cp + 12);
; #pragma unroll
;         for (int e = 0; e < 4; ++e) { h[e] = p0[e] * h[e] + s0[e]; h[4 + e] = p1[e] * h[4 + e] + s1[e]; } }
; }
; __device__ __forceinline__ void rg_scan2_phase(const bf16_t* RA0, bf16_t* RI0, const bf16_t* RA1, const bf16_t* RI1, const bf16_t* XCV, const float* bap, const float* bxp, const float* lamp, const float* CAR, bf16_t* Gb, int gtid, int ngt) {
;     ...
;         rg_fold8(CAR, b, 1, 2 * cbk, cg, h); rg_consts8(bap, bxp, lamp, 1280 + 8 * cg, ba, bx, sp);
.LBB0_1379:
	v_cmp_ne_u32_e32 vcc, v66, v64
	v_mov_b32_e32 v50, 0
	v_mov_b32_e32 v58, 0
	v_mov_b32_e32 v60, 0
	v_mov_b32_e32 v54, 0
	v_mov_b32_e32 v56, 0
	v_mov_b32_e32 v48, 0
	v_mov_b32_e32 v52, 0
	v_mov_b32_e32 v46, 0
	s_and_saveexec_b64 s[6:7], vcc
	s_cbranch_execz .LBB0_1383
	v_sub_u32_e32 v0, v66, v64
	s_movk_i32 s1, 0x90
	v_mov_b32_e32 v1, 0x48
	v_mov_b32_e32 v46, 0
	v_lshlrev_b32_e32 v0, 1, v0
	v_mad_i32_i24 v1, v65, s1, v1
	s_mov_b64 s[24:25], 0
	v_mov_b32_e32 v47, v46
	v_mov_b32_e32 v48, v46
	v_mov_b32_e32 v49, v46
	v_mov_b32_e32 v54, v46
	v_mov_b32_e32 v55, v46
	v_mov_b32_e32 v58, v46
	v_mov_b32_e32 v59, v46
	v_mad_i64_i32 v[160:161], s[2:3], v1, s41, v[28:29]
	v_lshlrev_b64 v[160:161], 6, v[160:161]
	v_lshl_add_u64 v[160:161], s[20:21], 0, v[160:161]
	global_load_dwordx4 v[96:99], v[160:161], off offset:48
	global_load_dwordx4 v[100:103], v[160:161], off offset:32
	global_load_dwordx4 v[104:107], v[160:161], off
	global_load_dwordx4 v[108:111], v[160:161], off offset:16
	v_add_u32_e32 v1, 1, v1
	v_mad_i64_i32 v[160:161], s[2:3], v1, s41, v[28:29]
	v_lshlrev_b64 v[160:161], 6, v[160:161]
	v_lshl_add_u64 v[160:161], s[20:21], 0, v[160:161]
	global_load_dwordx4 v[112:115], v[160:161], off offset:48
	global_load_dwordx4 v[116:119], v[160:161], off offset:32
	global_load_dwordx4 v[120:123], v[160:161], off
	global_load_dwordx4 v[124:127], v[160:161], off offset:16
	v_add_u32_e32 v1, 1, v1
	v_mad_i64_i32 v[160:161], s[2:3], v1, s41, v[28:29]
	v_lshlrev_b64 v[160:161], 6, v[160:161]
	v_lshl_add_u64 v[160:161], s[20:21], 0, v[160:161]
	global_load_dwordx4 v[128:131], v[160:161], off offset:48
	global_load_dwordx4 v[132:135], v[160:161], off offset:32
	global_load_dwordx4 v[136:139], v[160:161], off
	global_load_dwordx4 v[140:143], v[160:161], off offset:16
	v_add_u32_e32 v1, 1, v1
	v_mad_i64_i32 v[160:161], s[2:3], v1, s41, v[28:29]
	v_lshlrev_b64 v[160:161], 6, v[160:161]
	v_lshl_add_u64 v[160:161], s[20:21], 0, v[160:161]
	global_load_dwordx4 v[144:147], v[160:161], off offset:48
	global_load_dwordx4 v[148:151], v[160:161], off offset:32
	global_load_dwordx4 v[152:155], v[160:161], off
	global_load_dwordx4 v[156:159], v[160:161], off offset:16
	v_add_u32_e32 v1, 1, v1
.LBB0_1381:
	v_mad_i64_i32 v[160:161], s[2:3], v1, s41, v[28:29]
	v_lshlrev_b64 v[160:161], 6, v[160:161]
	v_lshl_add_u64 v[160:161], s[20:21], 0, v[160:161]
	global_load_dwordx4 v[168:171], v[160:161], off offset:48
	global_load_dwordx4 v[172:175], v[160:161], off offset:32
	global_load_dwordx4 v[176:179], v[160:161], off
	global_load_dwordx4 v[180:183], v[160:161], off offset:16
	v_add_u32_e32 v1, 1, v1
	v_add_u32_e32 v0, -1, v0
	v_cmp_eq_u32_e32 vcc, 0, v0
	s_nop 0
	s_or_b64 s[24:25], vcc, s[24:25]
	s_waitcnt vmcnt(16)
	v_pk_fma_f32 v[46:47], v[46:47], v[104:105], v[100:101]
	v_pk_fma_f32 v[54:55], v[54:55], v[108:109], v[96:97]
	v_pk_fma_f32 v[48:49], v[48:49], v[106:107], v[102:103]
	v_pk_fma_f32 v[58:59], v[58:59], v[110:111], v[98:99]
	s_andn2_b64 exec, exec, s[24:25]
	s_cbranch_execz .Lfold2_done
	v_mad_i64_i32 v[160:161], s[2:3], v1, s41, v[28:29]
	v_lshlrev_b64 v[160:161], 6, v[160:161]
	v_lshl_add_u64 v[160:161], s[20:21], 0, v[160:161]
	global_load_dwordx4 v[96:99], v[160:161], off offset:48
	global_load_dwordx4 v[100:103], v[160:161], off offset:32
	global_load_dwordx4 v[104:107], v[160:161], off
	global_load_dwordx4 v[108:111], v[160:161], off offset:16
	v_add_u32_e32 v1, 1, v1
	v_add_u32_e32 v0, -1, v0
	v_cmp_eq_u32_e32 vcc, 0, v0
	s_nop 0
	s_or_b64 s[24:25], vcc, s[24:25]
	s_waitcnt vmcnt(16)
	v_pk_fma_f32 v[46:47], v[46:47], v[120:121], v[116:117]
	v_pk_fma_f32 v[54:55], v[54:55], v[124:125], v[112:113]
	v_pk_fma_f32 v[48:49], v[48:49], v[122:123], v[118:119]
	v_pk_fma_f32 v[58:59], v[58:59], v[126:127], v[114:115]
	s_andn2_b64 exec, exec, s[24:25]
	s_cbranch_execz .Lfold2_done
	v_mad_i64_i32 v[160:161], s[2:3], v1, s41, v[28:29]
	v_lshlrev_b64 v[160:161], 6, v[160:161]
	v_lshl_add_u64 v[160:161], s[20:21], 0, v[160:161]
	global_load_dwordx4 v[112:115], v[160:161], off offset:48
	global_load_dwordx4 v[116:119], v[160:161], off offset:32
	global_load_dwordx4 v[120:123], v[160:161], off
	global_load_dwordx4 v[124:127], v[160:161], off offset:16
	v_add_u32_e32 v1, 1, v1
	v_add_u32_e32 v0, -1, v0
	v_cmp_eq_u32_e32 vcc, 0, v0
	s_nop 0
	s_or_b64 s[24:25], vcc, s[24:25]
	s_waitcnt vmcnt(16)
	v_pk_fma_f32 v[46:47], v[46:47], v[136:137], v[132:133]
	v_pk_fma_f32 v[54:55], v[54:55], v[140:141], v[128:129]
	v_pk_fma_f32 v[48:49], v[48:49], v[138:139], v[134:135]
	v_pk_fma_f32 v[58:59], v[58:59], v[142:143], v[130:131]
	s_andn2_b64 exec, exec, s[24:25]
	s_cbranch_execz .Lfold2_done
	v_mad_i64_i32 v[160:161], s[2:3], v1, s41, v[28:29]
	v_lshlrev_b64 v[160:161], 6, v[160:161]
	v_lshl_add_u64 v[160:161], s[20:21], 0, v[160:161]
	global_load_dwordx4 v[128:131], v[160:161], off offset:48
	global_load_dwordx4 v[132:135], v[160:161], off offset:32
	global_load_dwordx4 v[136:139], v[160:161], off
	global_load_dwordx4 v[140:143], v[160:161], off offset:16
	v_add_u32_e32 v1, 1, v1
	v_add_u32_e32 v0, -1, v0
	v_cmp_eq_u32_e32 vcc, 0, v0
	s_nop 0
	s_or_b64 s[24:25], vcc, s[24:25]
	s_waitcnt vmcnt(16)
	v_pk_fma_f32 v[46:47], v[46:47], v[152:153], v[148:149]
	v_pk_fma_f32 v[54:55], v[54:55], v[156:157], v[144:145]
	v_pk_fma_f32 v[48:49], v[48:49], v[154:155], v[150:151]
	v_pk_fma_f32 v[58:59], v[58:59], v[158:159], v[146:147]
	s_andn2_b64 exec, exec, s[24:25]
	s_cbranch_execz .Lfold2_done
	v_mad_i64_i32 v[160:161], s[2:3], v1, s41, v[28:29]
	v_lshlrev_b64 v[160:161], 6, v[160:161]
	v_lshl_add_u64 v[160:161], s[20:21], 0, v[160:161]
	global_load_dwordx4 v[144:147], v[160:161], off offset:48
	global_load_dwordx4 v[148:151], v[160:161], off offset:32
	global_load_dwordx4 v[152:155], v[160:161], off
	global_load_dwordx4 v[156:159], v[160:161], off offset:16
	v_add_u32_e32 v1, 1, v1
	v_add_u32_e32 v0, -1, v0
	v_cmp_eq_u32_e32 vcc, 0, v0
	s_nop 0
	s_or_b64 s[24:25], vcc, s[24:25]
	s_waitcnt vmcnt(16)
	v_pk_fma_f32 v[46:47], v[46:47], v[176:177], v[172:173]
	v_pk_fma_f32 v[54:55], v[54:55], v[180:181], v[168:169]
	v_pk_fma_f32 v[48:49], v[48:49], v[178:179], v[174:175]
	v_pk_fma_f32 v[58:59], v[58:59], v[182:183], v[170:171]
	s_andn2_b64 exec, exec, s[24:25]
	s_cbranch_execnz .LBB0_1381
